# v21
# speedup vs baseline: 1.0116x; 1.0062x over previous
; __device__ __forceinline__ unsigned xb_add(unsigned* p, unsigned v) { return __hip_atomic_fetch_add(p, v, __ATOMIC_RELAXED, __HIP_MEMORY_SCOPE_AGENT); }
; __device__ __forceinline__ void xcd_barrier(const XcdBarrier& b) {
;     asm volatile("s_waitcnt vmcnt(0)" ::: "memory");
;     __syncthreads();
;     if (threadIdx.x == 0) {
;         unsigned* bar = b.bar;
;         __builtin_amdgcn_s_waitcnt(0);
;         unsigned nloc = b.st[0], nx = b.st[1];
;         if (nloc == 0u) { xcd_barrier_complete(bar, b.x, nloc, nx); b.st[0] = nloc; b.st[1] = nx; }
;         const unsigned old = xb_add(&bar[XB_XSUB(b.x)], 1u);
.LBB0_813:
	s_mov_b32 s12, 0
	s_getreg_b32 s14, hwreg(HW_REG_XCC_ID, 0, 4)
	s_waitcnt vmcnt(0)
	s_waitcnt lgkmcnt(0)
	s_barrier
	s_and_saveexec_b64 s[6:7], s[4:5]
	s_cbranch_execz .LBB0_865
	v_writelane_b32 v16, s14, 0
	v_writelane_b32 v16, s15, 1
	v_writelane_b32 v16, s16, 2
	v_writelane_b32 v16, s17, 3
	v_writelane_b32 v16, s18, 4
	v_writelane_b32 v16, s19, 5
	v_writelane_b32 v16, s20, 6
	v_writelane_b32 v16, s21, 7
	v_writelane_b32 v16, s22, 8
	v_writelane_b32 v16, s23, 9
	v_writelane_b32 v16, s24, 10
	v_writelane_b32 v16, s25, 11
	v_mov_b32_e32 v10, 0x23f08
	ds_read_b32 v11, v10
	s_load_dwordx2 s[14:15], s[0:1], 0xc0
	s_waitcnt lgkmcnt(0)
	v_readfirstlane_b32 s16, v11
	s_cmp_eq_u32 s16, 1
	s_cbranch_scc1 .Llb_go_5
	s_cmp_eq_u32 s16, 2
	s_cbranch_scc1 .Llb_full_5
	s_mov_b64 s[18:19], exec
	s_mov_b64 exec, -1
	s_add_u32 s20, s14, 0x25d04000
	s_addc_u32 s21, s15, 0
	v_and_b32_e32 v2, 63, v234
	v_lshlrev_b32_e32 v3, 2, v2
	v_and_b32_e32 v9, 7, v2
	v_lshlrev_b32_e32 v9, 2, v9
	global_load_dword v4, v3, s[20:21] sc1
	global_load_dword v5, v3, s[20:21] offset:256 sc1
	global_load_dword v6, v3, s[20:21] offset:512 sc1
	global_load_dword v7, v3, s[20:21] offset:768 sc1
	global_load_dword v8, v9, s[20:21] sc1
	s_waitcnt vmcnt(0)
	v_cmp_eq_u32_e32 vcc, v4, v8
	s_mov_b64 s[24:25], vcc
	v_cmp_eq_u32_e32 vcc, v5, v8
	s_and_b64 s[24:25], s[24:25], vcc
	v_cmp_eq_u32_e32 vcc, v6, v8
	s_and_b64 s[24:25], s[24:25], vcc
	v_cmp_eq_u32_e32 vcc, v7, v8
	s_and_b64 s[24:25], s[24:25], vcc
	v_cmp_ne_u32_e32 vcc, 0, v8
	s_and_b64 s[24:25], s[24:25], vcc
	s_mov_b32 s16, 2
	s_cmp_eq_u64 s[24:25], exec
	s_cbranch_scc0 .Llb_dec_5
	s_cmpk_eq_i32 s46, 0x100
	s_cbranch_scc0 .Llb_dec_5
	s_mov_b32 s16, 1

; __device__ __forceinline__ unsigned xb_ld(unsigned* p)              { return __hip_atomic_load(p, __ATOMIC_RELAXED, __HIP_MEMORY_SCOPE_AGENT); }
; __device__ __forceinline__ unsigned xb_add(unsigned* p, unsigned v) { return __hip_atomic_fetch_add(p, v, __ATOMIC_RELAXED, __HIP_MEMORY_SCOPE_AGENT); }
; #define XB_SPIN(cond, bar) do { unsigned _sp = 0; while (cond) { __builtin_amdgcn_s_sleep(1); \
;     if ((++_sp & 255u) == 0u) { if (xb_ld(&(bar)[XB_TMO])) break; if (_sp > XB_SPIN_CAP) { atomicAdd(&(bar)[XB_TMO], 1u); break; } } } } while (0)
; __device__ __forceinline__ void xcd_barrier(const XcdBarrier& b) {
;     ...
;         const unsigned old = xb_add(&bar[XB_XSUB(b.x)], 1u);
;         const unsigned gen = old / nloc;
;         if (old + 1u == (gen + 1u) * nloc) {
;             __builtin_amdgcn_fence(__ATOMIC_RELEASE, "agent");
;             asm volatile("s_waitcnt vmcnt(0)" ::: "memory");
;             const unsigned og = xb_add(&bar[XB_TOP], 1u);
;             const unsigned tg = og / nx;
;             if (og + 1u == (tg + 1u) * nx) xb_add(&bar[XB_TOPGEN], 1u);
;             else XB_SPIN(xb_ld(&bar[XB_TOPGEN]) == tg, bar);
;             __builtin_amdgcn_fence(__ATOMIC_ACQUIRE, "agent");
;             xb_add(&bar[XB_XGEN(b.x)], 1u);
;             asm volatile("s_waitcnt vmcnt(0)" ::: "memory");
;         } else {
;             XB_SPIN(xb_ld(&bar[XB_XGEN(b.x)]) == gen, bar);
;             __builtin_amdgcn_fence(__ATOMIC_ACQUIRE, "agent");
;             asm volatile("s_waitcnt vmcnt(0)" ::: "memory");
;         }
.Llb_go_5:
	s_add_u32 s22, s14, 0x25d06000
	s_addc_u32 s23, s15, 0
	v_mov_b32_e32 v2, 0
	v_mov_b32_e32 v3, 1
	global_atomic_add v2, v3, s[22:23]
	s_and_b32 s16, s2, 7
	s_lshl_b32 s16, s16, 8
	s_add_u32 s20, s14, 0x25d05000
	s_addc_u32 s21, s15, 0
	s_add_u32 s20, s20, s16
	s_addc_u32 s21, s21, 0
	v_mov_b32_e32 v2, 0
	v_mov_b32_e32 v3, 1
	global_atomic_add v4, v2, v3, s[20:21] sc0
	s_waitcnt vmcnt(0)
	v_readfirstlane_b32 s17, v4
	s_lshr_b32 s22, s17, 5
	s_add_u32 s17, s17, 1
	s_and_b32 s17, s17, 31
	s_cmp_eq_u32 s17, 0
	s_cbranch_scc0 .Llb_wait_5
	global_atomic_add v2, v3, s[20:21] offset:2048
	s_branch .Llb_acq_5

; __device__ __forceinline__ unsigned xb_ld(unsigned* p)              { return __hip_atomic_load(p, __ATOMIC_RELAXED, __HIP_MEMORY_SCOPE_AGENT); }
; __device__ __forceinline__ void xcd_barrier_complete(unsigned* bar, unsigned x, unsigned& nloc, unsigned& nx) {
;     const unsigned G = gridDim.x * gridDim.y * gridDim.z;
;     unsigned sum, cnt, mine, sp = 0u;
;     for (;;) {
;         sum = 0u; cnt = 0u; mine = 0u;
; #pragma unroll
;         for (unsigned j = 0; j < 16; ++j) { const unsigned c = xb_ld(&bar[XB_XCNT(j)]); sum += c; cnt += (c > 0u) ? 1u : 0u; mine = (j == x) ? c : mine; }
;         if (sum == G) break;
;         __builtin_amdgcn_s_sleep(1);
;         if ((++sp & 255u) == 0u) { if (xb_ld(&bar[XB_TMO])) break; if (sp > XB_SPIN_CAP) { atomicAdd(&bar[XB_TMO], 1u); break; } }
;     }
;     nloc = mine > 0u ? mine : 1u; nx = cnt > 0u ? cnt : 1u;
; }
; __device__ __forceinline__ void xcd_barrier(const XcdBarrier& b) {
;     asm volatile("s_waitcnt vmcnt(0)" ::: "memory");
;     __syncthreads();
;     if (threadIdx.x == 0) {
;         unsigned* bar = b.bar;
;         __builtin_amdgcn_s_waitcnt(0);
;         unsigned nloc = b.st[0], nx = b.st[1];
;         if (nloc == 0u) { xcd_barrier_complete(bar, b.x, nloc, nx); b.st[0] = nloc; b.st[1] = nx; }
.Llb_full_5:
	v_readlane_b32 s14, v16, 0
	v_readlane_b32 s15, v16, 1
	v_readlane_b32 s16, v16, 2
	v_readlane_b32 s17, v16, 3
	v_readlane_b32 s18, v16, 4
	v_readlane_b32 s19, v16, 5
	v_readlane_b32 s20, v16, 6
	v_readlane_b32 s21, v16, 7
	v_readlane_b32 s22, v16, 8
	v_readlane_b32 s23, v16, 9
	v_readlane_b32 s24, v16, 10
	v_readlane_b32 s25, v16, 11
	s_nop 4
	s_ashr_i32 s13, s12, 31
	s_lshl_b64 s[10:11], s[12:13], 2
	s_add_u32 s10, s24, s10
	s_addc_u32 s11, s25, s11
	s_add_u32 s10, s10, 0x25d00000
	s_addc_u32 s11, s11, 0
	s_add_i32 s27, s12, 0
	s_add_i32 s27, s27, 0x23f00
	v_mov_b32_e32 v0, s27
	s_waitcnt vmcnt(0) expcnt(0) lgkmcnt(0)
	ds_read_b32 v2, v0
	ds_read_b32 v0, v0 offset:4
	s_and_b32 s26, s14, 15
	s_waitcnt lgkmcnt(1)
	v_cmp_ne_u32_e32 vcc, 0, v2
	s_cbranch_vccnz .LBB0_829
	s_add_u32 s12, s10, 0x1000
	s_addc_u32 s13, s11, 0
	s_add_u32 s14, s10, 0x1100
	s_addc_u32 s15, s11, 0
	s_add_u32 s16, s10, 0x1200
	s_addc_u32 s17, s11, 0
	s_mul_i32 s28, s47, s94
	s_add_u32 s18, s10, 0x1300
	s_mul_i32 s28, s28, s46
	s_addc_u32 s19, s11, 0
	s_mov_b32 s29, 1
	v_mov_b32_e32 v16, 0
	s_branch .LBB0_817

; __device__ __forceinline__ unsigned xb_ld(unsigned* p)              { return __hip_atomic_load(p, __ATOMIC_RELAXED, __HIP_MEMORY_SCOPE_AGENT); }
; __device__ __forceinline__ unsigned xb_add(unsigned* p, unsigned v) { return __hip_atomic_fetch_add(p, v, __ATOMIC_RELAXED, __HIP_MEMORY_SCOPE_AGENT); }
; #define XB_SPIN(cond, bar) do { unsigned _sp = 0; while (cond) { __builtin_amdgcn_s_sleep(1); \
;     if ((++_sp & 255u) == 0u) { if (xb_ld(&(bar)[XB_TMO])) break; if (_sp > XB_SPIN_CAP) { atomicAdd(&(bar)[XB_TMO], 1u); break; } } } } while (0)
; __device__ __forceinline__ void xcd_barrier(const XcdBarrier& b) {
;     ...
;         const unsigned old = xb_add(&bar[XB_XSUB(b.x)], 1u);
;         const unsigned gen = old / nloc;
;         if (old + 1u == (gen + 1u) * nloc) {
;             __builtin_amdgcn_fence(__ATOMIC_RELEASE, "agent");
;             asm volatile("s_waitcnt vmcnt(0)" ::: "memory");
;             const unsigned og = xb_add(&bar[XB_TOP], 1u);
;             const unsigned tg = og / nx;
;             if (og + 1u == (tg + 1u) * nx) xb_add(&bar[XB_TOPGEN], 1u);
;             else XB_SPIN(xb_ld(&bar[XB_TOPGEN]) == tg, bar);
;             __builtin_amdgcn_fence(__ATOMIC_ACQUIRE, "agent");
;             xb_add(&bar[XB_XGEN(b.x)], 1u);
;             asm volatile("s_waitcnt vmcnt(0)" ::: "memory");
;         } else {
;             XB_SPIN(xb_ld(&bar[XB_XGEN(b.x)]) == gen, bar);
;             __builtin_amdgcn_fence(__ATOMIC_ACQUIRE, "agent");
;             asm volatile("s_waitcnt vmcnt(0)" ::: "memory");
;         }
.Llb_go_6:
	s_add_u32 s22, s14, 0x25d06000
	s_addc_u32 s23, s15, 0
	v_mov_b32_e32 v2, 0
	s_mov_b32 s24, 0
.Llb_gw_6:
	global_load_dword v4, v2, s[22:23] sc1
	s_waitcnt vmcnt(0)
	v_readfirstlane_b32 s25, v4
	s_cmp_ge_u32 s25, 256
	s_cbranch_scc1 .Llb_gd_6
	s_sleep 1
	s_add_u32 s24, s24, 1
	s_cmp_lt_u32 s24, 0x100000
	s_cbranch_scc1 .Llb_gw_6

; __device__ __forceinline__ unsigned xb_add(unsigned* p, unsigned v) { return __hip_atomic_fetch_add(p, v, __ATOMIC_RELAXED, __HIP_MEMORY_SCOPE_AGENT); }
; __device__ __forceinline__ void xcd_barrier(const XcdBarrier& b) {
;     asm volatile("s_waitcnt vmcnt(0)" ::: "memory");
;     __syncthreads();
;     if (threadIdx.x == 0) {
;         unsigned* bar = b.bar;
;         __builtin_amdgcn_s_waitcnt(0);
;         unsigned nloc = b.st[0], nx = b.st[1];
;         if (nloc == 0u) { xcd_barrier_complete(bar, b.x, nloc, nx); b.st[0] = nloc; b.st[1] = nx; }
;         const unsigned old = xb_add(&bar[XB_XSUB(b.x)], 1u);
.LBB0_1901:
	s_mov_b32 s14, 0
	s_getreg_b32 s10, hwreg(HW_REG_XCC_ID, 0, 4)
	s_waitcnt vmcnt(0)
	v_readlane_b32 s72, v254, 4
	v_readlane_b32 s73, v254, 5
	s_waitcnt lgkmcnt(0)
	s_barrier
	s_and_saveexec_b64 s[8:9], s[4:5]
	s_cbranch_execz .LBB0_1953
	v_writelane_b32 v16, s14, 0
	v_writelane_b32 v16, s15, 1
	v_writelane_b32 v16, s16, 2
	v_writelane_b32 v16, s17, 3
	v_writelane_b32 v16, s18, 4
	v_writelane_b32 v16, s19, 5
	v_writelane_b32 v16, s20, 6
	v_writelane_b32 v16, s21, 7
	v_writelane_b32 v16, s22, 8
	v_writelane_b32 v16, s23, 9
	v_writelane_b32 v16, s24, 10
	v_writelane_b32 v16, s25, 11
	v_mov_b32_e32 v10, 0x23f08
	ds_read_b32 v11, v10
	s_load_dwordx2 s[14:15], s[0:1], 0xc0
	s_waitcnt lgkmcnt(0)
	v_readfirstlane_b32 s16, v11
	s_cmp_eq_u32 s16, 1
	s_cbranch_scc1 .Llb_go_14
	s_cmp_eq_u32 s16, 2
	s_cbranch_scc1 .Llb_full_14
	s_mov_b64 s[18:19], exec
	s_mov_b64 exec, -1
	s_add_u32 s20, s14, 0x25d04000
	s_addc_u32 s21, s15, 0
	v_and_b32_e32 v2, 63, v234
	v_lshlrev_b32_e32 v3, 2, v2
	v_and_b32_e32 v9, 7, v2
	v_lshlrev_b32_e32 v9, 2, v9
	global_load_dword v4, v3, s[20:21] sc1
	global_load_dword v5, v3, s[20:21] offset:256 sc1
	global_load_dword v6, v3, s[20:21] offset:512 sc1
	global_load_dword v7, v3, s[20:21] offset:768 sc1
	global_load_dword v8, v9, s[20:21] sc1
	s_waitcnt vmcnt(0)
	v_cmp_eq_u32_e32 vcc, v4, v8
	s_mov_b64 s[24:25], vcc
	v_cmp_eq_u32_e32 vcc, v5, v8
	s_and_b64 s[24:25], s[24:25], vcc
	v_cmp_eq_u32_e32 vcc, v6, v8
	s_and_b64 s[24:25], s[24:25], vcc
	v_cmp_eq_u32_e32 vcc, v7, v8
	s_and_b64 s[24:25], s[24:25], vcc
	v_cmp_ne_u32_e32 vcc, 0, v8
	s_and_b64 s[24:25], s[24:25], vcc
	s_mov_b32 s16, 2
	s_cmp_eq_u64 s[24:25], exec
	s_cbranch_scc0 .Llb_dec_14
	s_cmpk_eq_i32 s46, 0x100
	s_cbranch_scc0 .Llb_dec_14
	s_mov_b32 s16, 1

; __device__ __forceinline__ unsigned xb_ld(unsigned* p)              { return __hip_atomic_load(p, __ATOMIC_RELAXED, __HIP_MEMORY_SCOPE_AGENT); }
; __device__ __forceinline__ void xcd_barrier_complete(unsigned* bar, unsigned x, unsigned& nloc, unsigned& nx) {
;     const unsigned G = gridDim.x * gridDim.y * gridDim.z;
;     unsigned sum, cnt, mine, sp = 0u;
;     for (;;) {
;         sum = 0u; cnt = 0u; mine = 0u;
; #pragma unroll
;         for (unsigned j = 0; j < 16; ++j) { const unsigned c = xb_ld(&bar[XB_XCNT(j)]); sum += c; cnt += (c > 0u) ? 1u : 0u; mine = (j == x) ? c : mine; }
;         if (sum == G) break;
;         __builtin_amdgcn_s_sleep(1);
;         if ((++sp & 255u) == 0u) { if (xb_ld(&bar[XB_TMO])) break; if (sp > XB_SPIN_CAP) { atomicAdd(&bar[XB_TMO], 1u); break; } }
;     }
;     nloc = mine > 0u ? mine : 1u; nx = cnt > 0u ? cnt : 1u;
; }
; __device__ __forceinline__ void xcd_barrier(const XcdBarrier& b) {
;     asm volatile("s_waitcnt vmcnt(0)" ::: "memory");
;     __syncthreads();
;     if (threadIdx.x == 0) {
;         unsigned* bar = b.bar;
;         __builtin_amdgcn_s_waitcnt(0);
;         unsigned nloc = b.st[0], nx = b.st[1];
;         if (nloc == 0u) { xcd_barrier_complete(bar, b.x, nloc, nx); b.st[0] = nloc; b.st[1] = nx; }
.Llb_full_14:
	v_readlane_b32 s14, v16, 0
	v_readlane_b32 s15, v16, 1
	v_readlane_b32 s16, v16, 2
	v_readlane_b32 s17, v16, 3
	v_readlane_b32 s18, v16, 4
	v_readlane_b32 s19, v16, 5
	v_readlane_b32 s20, v16, 6
	v_readlane_b32 s21, v16, 7
	v_readlane_b32 s22, v16, 8
	v_readlane_b32 s23, v16, 9
	v_readlane_b32 s24, v16, 10
	v_readlane_b32 s25, v16, 11
	s_nop 4
	s_ashr_i32 s15, s14, 31
	s_lshl_b64 s[12:13], s[14:15], 2
	s_add_u32 s11, s24, s12
	s_addc_u32 s13, s25, s13
	s_add_u32 s12, s11, 0x25d00000
	s_addc_u32 s13, s13, 0
	s_add_i32 s11, s14, 0
	s_add_i32 s11, s11, 0x23f00
	v_mov_b32_e32 v0, s11
	s_waitcnt vmcnt(0) expcnt(0) lgkmcnt(0)
	ds_read_b32 v2, v0
	ds_read_b32 v0, v0 offset:4
	s_and_b32 s10, s10, 15
	s_waitcnt lgkmcnt(1)
	v_cmp_ne_u32_e32 vcc, 0, v2
	s_cbranch_vccnz .LBB0_1917
	s_add_u32 s14, s12, 0x1000
	s_addc_u32 s15, s13, 0
	s_add_u32 s16, s12, 0x1100
	s_addc_u32 s17, s13, 0
	s_add_u32 s18, s12, 0x1200
	s_addc_u32 s19, s13, 0
	s_mul_i32 s28, s47, s94
	s_add_u32 s20, s12, 0x1300
	s_mul_i32 s28, s28, s46
	s_addc_u32 s21, s13, 0
	s_mov_b32 s29, 1
	v_mov_b32_e32 v16, 0
	s_branch .LBB0_1905

; __device__ __forceinline__ unsigned xb_ld(unsigned* p)              { return __hip_atomic_load(p, __ATOMIC_RELAXED, __HIP_MEMORY_SCOPE_AGENT); }
; __device__ __forceinline__ unsigned xb_add(unsigned* p, unsigned v) { return __hip_atomic_fetch_add(p, v, __ATOMIC_RELAXED, __HIP_MEMORY_SCOPE_AGENT); }
; #define XB_SPIN(cond, bar) do { unsigned _sp = 0; while (cond) { __builtin_amdgcn_s_sleep(1); \
;     if ((++_sp & 255u) == 0u) { if (xb_ld(&(bar)[XB_TMO])) break; if (_sp > XB_SPIN_CAP) { atomicAdd(&(bar)[XB_TMO], 1u); break; } } } } while (0)
; __device__ __forceinline__ void xcd_barrier(const XcdBarrier& b) {
;     ...
;         const unsigned old = xb_add(&bar[XB_XSUB(b.x)], 1u);
;         const unsigned gen = old / nloc;
;         if (old + 1u == (gen + 1u) * nloc) {
;             __builtin_amdgcn_fence(__ATOMIC_RELEASE, "agent");
;             asm volatile("s_waitcnt vmcnt(0)" ::: "memory");
;             const unsigned og = xb_add(&bar[XB_TOP], 1u);
;             const unsigned tg = og / nx;
;             if (og + 1u == (tg + 1u) * nx) xb_add(&bar[XB_TOPGEN], 1u);
;             else XB_SPIN(xb_ld(&bar[XB_TOPGEN]) == tg, bar);
;             __builtin_amdgcn_fence(__ATOMIC_ACQUIRE, "agent");
;             xb_add(&bar[XB_XGEN(b.x)], 1u);
;             asm volatile("s_waitcnt vmcnt(0)" ::: "memory");
;         } else {
;             XB_SPIN(xb_ld(&bar[XB_XGEN(b.x)]) == gen, bar);
;             __builtin_amdgcn_fence(__ATOMIC_ACQUIRE, "agent");
;             asm volatile("s_waitcnt vmcnt(0)" ::: "memory");
;         }
.Llb_gw_15:
	global_load_dword v4, v2, s[22:23] sc1
	s_waitcnt vmcnt(0)
	v_readfirstlane_b32 s25, v4
	s_cmp_ge_u32 s25, 512
	s_cbranch_scc1 .Llb_gd_15
	s_sleep 1
	s_add_u32 s24, s24, 1
	s_cmp_lt_u32 s24, 0x100000
	s_cbranch_scc1 .Llb_gw_15
